# scan phase: scanner waves (one per SIMD, critical path) run at s_setprio 3 over the stager waves
# speedup vs baseline: 1.1734x; 1.0043x over previous
; __device__ __forceinline__ void scan_phase(const Params& p, int cidx, int task_lo, int task_hi) {
;     ...
;   const int rolew = __builtin_amdgcn_readfirstlane(s_role2[wave]);
;   const bool stat = (gridDim.x == 256 && task_lo == 0);
;   bool first = true;
;   while (true) {
;     __syncthreads();
;     if (tid == 0) s_task = (stat && first && blockIdx.x < 192) ? -1 : atomicAdd(counter, 1);
;     __syncthreads();
;     const int tq = __builtin_amdgcn_readfirstlane(s_task);
;     first = false;
;     const int task = (tq < 0) ? ((int)(blockIdx.x & 7) * 24 + (int)(blockIdx.x >> 3)) : (tq + (stat ? 192 : task_lo));
;     if (task >= task_hi) break;
;     int b, h, half, row0, T;
;     bool sample;
;     if (task < 192) { b = task / 24; h = (task % 24) >> 1; half = task & 1; row0 = b * 2048; T = 2048; sample = false; }
;     else { int u = task - 192; b = u / 24; h = (u % 24) >> 1; half = u & 1; row0 = NP + b * 4; T = 4; sample = true; }
;     const int nch = (T + TC - 1) / TC;
;     const int sbase = half * 32 + (rolew & 3) * 8;
;     const int srow = sbase + (lane >> 3);
;     const int j8 = (lane & 7) * 8;
;     float* obuf = obufs + (rolew & 3) * 128;
.LBB0_625:
	s_or_b64 exec, exec, s[2:3]
	s_add_u32 s0, s96, 0x2e00000
	s_addc_u32 s1, s97, 0
	s_lshl_b32 s2, s6, 2
	s_add_i32 s2, s2, 0x1c020
	v_mov_b32_e32 v0, s2
	v_readlane_b32 s5, v254, 0
	s_waitcnt lgkmcnt(0)
	s_barrier
	ds_read_b32 v0, v0
	s_cmpk_lt_u32 s5, 0xc0
	s_cselect_b64 s[6:7], -1, 0
	s_cmpk_eq_i32 s42, 0x100
	s_cselect_b64 s[24:25], -1, 0
	s_and_b64 s[2:3], s[24:25], exec
	s_cselect_b32 s34, 0xc0, 0
	s_and_b32 s2, s5, 7
	s_waitcnt lgkmcnt(0)
	v_readfirstlane_b32 s4, v0
	s_mul_i32 s35, s2, 24
	s_lshr_b32 s2, s5, 3
	s_add_i32 s35, s35, s2
	s_and_b32 s2, s4, 3
	s_lshl_b32 s36, s2, 3
	s_lshl_b32 s8, s2, 9
	s_cmp_gt_i32 s4, 3
	s_cselect_b64 s[12:13], -1, 0
	s_cbranch_scc1 .Lscan_prio_skip
	s_setprio 3
.Lscan_prio_skip:
	s_add_i32 s4, s4, -4
	v_readlane_b32 s76, v254, 22
	v_lshrrev_b32_e32 v114, 5, v156
	s_lshl_b32 s5, s4, 2
	v_readlane_b32 s80, v254, 26
	v_readlane_b32 s81, v254, 27
	v_or_b32_e32 v115, s5, v114
	s_add_i32 s10, s5, 16
	s_add_i32 s5, s5, 32
	v_readlane_b32 s82, v254, 28
	v_readlane_b32 s83, v254, 29
	s_mov_b64 s[20:21], s[80:81]
	s_cmp_eq_u32 s4, 0
	s_mov_b64 s[22:23], s[82:83]
	s_cselect_b64 s[14:15], -1, 0
	s_add_u32 s16, s22, 0x1800
	s_addc_u32 s17, s23, 0
	v_or_b32_e32 v123, s10, v114
	s_add_u32 s10, s96, 0x7108100
	s_addc_u32 s11, s97, 0
	v_or_b32_e32 v117, 2, v115
	v_and_b32_e32 v2, 31, v128
	s_add_u32 s18, s96, 0xd408100
	v_lshlrev_b32_e32 v1, 3, v128
	v_lshlrev_b32_e32 v4, 3, v2
	v_cmp_gt_u32_e64 s[2:3], 2, v2
	v_lshlrev_b32_e32 v5, 3, v115
	v_lshlrev_b32_e32 v2, 2, v2
	v_lshlrev_b32_e32 v121, 3, v117
	v_lshrrev_b32_e32 v131, 2, v156
	s_addc_u32 s19, s97, 0
	v_and_b32_e32 v100, 56, v1
	v_add_u32_e32 v119, v5, v2
	v_add_u32_e32 v122, v121, v2
	v_sub_u32_e32 v127, v4, v2
	v_lshlrev_b32_e32 v2, 5, v131
	v_and_b32_e32 v1, 24, v1
	s_add_u32 s20, s96, 0x2f08100
	v_mov_b32_e32 v105, 0
	s_movk_i32 s37, 0x600
	v_or3_b32 v132, s8, v2, v1
	v_lshlrev_b32_e32 v104, 2, v100
	s_addc_u32 s21, s97, 0
	v_and_b32_e32 v1, 3, v128
	v_lshlrev_b32_e32 v0, 1, v128
	s_waitcnt vmcnt(0)
	v_mul_lo_u32 v3, v115, s37
	v_or_b32_e32 v129, 2, v114
	v_lshl_add_u64 v[106:107], s[68:69], 0, v[104:105]
	s_add_u32 s22, s96, 0x47c8100
	v_lshlrev_b32_e32 v104, 2, v1
	v_lshrrev_b32_e32 v101, 3, v156
	v_and_b32_e32 v103, 62, v0
	v_cmp_eq_u32_e32 vcc, 0, v115
	v_and_b32_e32 v0, 1, v128
	v_or_b32_e32 v118, v4, v3
	v_or_b32_e32 v125, s5, v114
	v_mul_u32_u24_e32 v6, 0x600, v114
	v_lshlrev_b32_e32 v7, 3, v114
	v_lshlrev_b32_e32 v8, 3, v129
	s_addc_u32 s23, s97, 0
	s_and_b64 s[24:25], s[6:7], s[24:25]
	v_lshl_add_u64 v[2:3], s[96:97], 0, v[104:105]
	s_mov_b64 s[6:7], 0x5008300
	v_readlane_b32 s68, v254, 20
	s_mov_b32 s9, 0
	v_cndmask_b32_e64 v102, 1.0, 0, vcc
	v_max_u32_e32 v116, 1, v115
	v_add_u32_e32 v120, 0xc00, v118
	v_or_b32_e32 v124, 2, v123
	v_or_b32_e32 v126, 2, v125
	v_cmp_gt_u32_e64 s[4:5], 32, v156
	v_lshl_or_b32 v130, v101, 2, s8
	v_lshl_add_u64 v[108:109], v[2:3], 0, s[6:7]
	s_mov_b64 s[26:27], -1
	v_mov_b32_e32 v133, 0x1c060
	s_movk_i32 s38, 0x1600
	v_add_u32_e32 v134, v127, v7
	v_add_u32_e32 v135, v127, v8
	v_lshlrev_b32_e32 v104, 2, v0
	v_add_u32_e32 v136, 0x6000, v118
	v_add_u32_e32 v137, v127, v5
	v_add_u32_e32 v138, v4, v6
	v_readlane_b32 s69, v254, 21
	v_readlane_b32 s77, v254, 23
	v_readlane_b32 s78, v254, 24
	v_readlane_b32 s79, v254, 25
	v_readlane_b32 s84, v254, 30
	v_readlane_b32 s85, v254, 31
	v_readlane_b32 s86, v254, 32
	v_readlane_b32 s87, v254, 33
	v_readlane_b32 s88, v254, 34
	v_readlane_b32 s89, v254, 35
	v_readlane_b32 s90, v254, 36
	v_readlane_b32 s91, v254, 37
	s_branch .LBB0_629

; __device__ __forceinline__ unsigned xb_ld(unsigned* p)              { return __hip_atomic_load(p, __ATOMIC_RELAXED, __HIP_MEMORY_SCOPE_AGENT); }
; __device__ __forceinline__ void xcd_barrier_complete(unsigned* bar, unsigned x, unsigned& nloc, unsigned& nx) {
;     const unsigned G = gridDim.x * gridDim.y * gridDim.z;
;     unsigned sum, cnt, mine, sp = 0u;
;     for (;;) {
;         sum = 0u; cnt = 0u; mine = 0u;
; #pragma unroll
;         for (unsigned j = 0; j < 16; ++j) { const unsigned c = xb_ld(&bar[XB_XCNT(j)]); sum += c; cnt += (c > 0u) ? 1u : 0u; mine = (j == x) ? c : mine; }
; __device__ __forceinline__ void xcd_barrier(const XcdBarrier& b) {
;     asm volatile("s_waitcnt vmcnt(0)" ::: "memory");
;     __syncthreads();
;     if (threadIdx.x == 0) {
;         unsigned* bar = b.bar;
;         __builtin_amdgcn_s_waitcnt(0);
;         unsigned nloc = b.st[0], nx = b.st[1];
;         if (nloc == 0u) { xcd_barrier_complete(bar, b.x, nloc, nx); b.st[0] = nloc; b.st[1] = nx; }
.LBB0_948:
	s_setprio 0
	s_cmp_lt_i32 s40, 8
	s_cselect_b64 s[4:5], -1, 0
	s_cmp_gt_i32 s40, 7
	s_cselect_b64 s[0:1], -1, 0
	s_cmp_lt_i32 s41, 7
	s_cselect_b64 s[2:3], -1, 0
	s_or_b64 s[0:1], s[0:1], s[2:3]
	v_readlane_b32 s68, v254, 20
	s_and_b64 vcc, exec, s[0:1]
	v_readlane_b32 s69, v254, 21
	s_cbranch_vccnz .LBB0_1036
	s_andn2_b64 vcc, exec, s[44:45]
	s_cbranch_vccnz .LBB0_999
	s_waitcnt vmcnt(0)
	s_waitcnt vmcnt(63) expcnt(7) lgkmcnt(15)
	s_barrier
	s_and_saveexec_b64 s[0:1], s[68:69]
	s_cbranch_execz .LBB0_998
	v_mov_b32_e32 v0, 0x1c040
	s_waitcnt vmcnt(0) expcnt(0) lgkmcnt(0)
	ds_read_b32 v2, v0
	v_mov_b32_e32 v0, 0x1c044
	ds_read_b32 v0, v0
	s_waitcnt lgkmcnt(1)
	v_cmp_ne_u32_e32 vcc, 0, v2
	s_cbranch_vccnz .LBB0_966
	v_readlane_b32 s2, v254, 17
	s_mul_i32 s33, s43, s2
	s_add_u32 s2, s96, 0xf928300
	s_addc_u32 s3, s97, 0
	s_add_u32 s6, s96, 0xf928500
	s_addc_u32 s7, s97, 0
	s_add_u32 s8, s96, 0xf928600
	s_addc_u32 s9, s97, 0
	s_add_u32 s10, s96, 0xf928700
	s_addc_u32 s11, s97, 0
	s_add_u32 s12, s96, 0xf928800
	s_addc_u32 s13, s97, 0
	s_add_u32 s14, s96, 0xf928900
	s_addc_u32 s15, s97, 0
	s_add_u32 s16, s96, 0xf928a00
	s_addc_u32 s17, s97, 0
	s_add_u32 s18, s96, 0xf928b00
	s_addc_u32 s19, s97, 0
	s_add_u32 s20, s96, 0xf928c00
	s_addc_u32 s21, s97, 0
	s_add_u32 s22, s96, 0xf928d00
	s_addc_u32 s23, s97, 0
	s_add_u32 s24, s96, 0xf928e00
	s_addc_u32 s25, s97, 0
	s_add_u32 s26, s96, 0xf928f00
	s_addc_u32 s27, s97, 0
	s_add_u32 s28, s96, 0xf929000
	s_addc_u32 s29, s97, 0
	s_add_u32 s30, s96, 0xf929100
	s_addc_u32 s31, s97, 0
	s_add_u32 s34, s96, 0xf929200
	s_addc_u32 s35, s97, 0
	s_add_u32 s36, s96, 0xf929300
	s_addc_u32 s37, s97, 0
	s_add_u32 s38, s96, 0xf929400
	s_mul_i32 s33, s33, s42
	s_addc_u32 s39, s97, 0
	s_mov_b32 s50, 1
	v_mov_b32_e32 v16, 0
	s_branch .LBB0_954
